# GEMM unit headers: the 128 accumulator registers cleared with 64 v_mov_b64 instead of 128 v_mov_b32 (five of the six GEMM instances)
# baseline (speedup 1.0000x reference)
.LBB0_402:
	s_add_u32 s7, s14, 0x100
	v_mov_b64_e32 v[34:35], 0
	s_addc_u32 s36, s15, 0
	s_mov_b32 s37, -2
	v_mov_b64_e32 v[36:37], 0
	v_mov_b64_e32 v[50:51], 0
	v_mov_b64_e32 v[52:53], 0
	v_mov_b64_e32 v[42:43], 0
	v_mov_b64_e32 v[44:45], 0
	v_mov_b64_e32 v[58:59], 0
	v_mov_b64_e32 v[60:61], 0
	v_mov_b64_e32 v[38:39], 0
	v_mov_b64_e32 v[40:41], 0
	v_mov_b64_e32 v[54:55], 0
	v_mov_b64_e32 v[56:57], 0
	v_mov_b64_e32 v[46:47], 0
	v_mov_b64_e32 v[48:49], 0
	v_mov_b64_e32 v[62:63], 0
	v_mov_b64_e32 v[64:65], 0
	v_mov_b64_e32 v[98:99], 0
	v_mov_b64_e32 v[100:101], 0
	v_mov_b64_e32 v[114:115], 0
	v_mov_b64_e32 v[116:117], 0
	v_mov_b64_e32 v[106:107], 0
	v_mov_b64_e32 v[108:109], 0
	v_mov_b64_e32 v[122:123], 0
	v_mov_b64_e32 v[124:125], 0
	v_mov_b64_e32 v[102:103], 0
	v_mov_b64_e32 v[104:105], 0
	v_mov_b64_e32 v[118:119], 0
	v_mov_b64_e32 v[120:121], 0
	v_mov_b64_e32 v[110:111], 0
	v_mov_b64_e32 v[112:113], 0
	v_mov_b64_e32 v[126:127], 0
	v_mov_b64_e32 v[128:129], 0
	v_mov_b64_e32 v[66:67], 0
	v_mov_b64_e32 v[68:69], 0
	v_mov_b64_e32 v[82:83], 0
	v_mov_b64_e32 v[84:85], 0
	v_mov_b64_e32 v[74:75], 0
	v_mov_b64_e32 v[76:77], 0
	v_mov_b64_e32 v[90:91], 0
	v_mov_b64_e32 v[92:93], 0
	v_mov_b64_e32 v[70:71], 0
	v_mov_b64_e32 v[72:73], 0
	v_mov_b64_e32 v[86:87], 0
	v_mov_b64_e32 v[88:89], 0
	v_mov_b64_e32 v[78:79], 0
	v_mov_b64_e32 v[80:81], 0
	v_mov_b64_e32 v[94:95], 0
	v_mov_b64_e32 v[96:97], 0
	v_mov_b64_e32 v[130:131], 0
	v_mov_b64_e32 v[132:133], 0
	v_mov_b64_e32 v[146:147], 0
	v_mov_b64_e32 v[148:149], 0
	v_mov_b64_e32 v[138:139], 0
	v_mov_b64_e32 v[140:141], 0
	v_mov_b64_e32 v[154:155], 0
	v_mov_b64_e32 v[156:157], 0
	v_mov_b64_e32 v[134:135], 0
	v_mov_b64_e32 v[136:137], 0
	v_mov_b64_e32 v[150:151], 0
	v_mov_b64_e32 v[152:153], 0
	v_mov_b64_e32 v[142:143], 0
	v_mov_b64_e32 v[144:145], 0
	v_mov_b64_e32 v[158:159], 0
	v_mov_b64_e32 v[160:161], 0

.LBB0_957:
	s_add_u32 s35, s12, 0x100
	v_mov_b64_e32 v[0:1], 0
	s_addc_u32 s36, s13, 0
	s_mov_b32 s37, -2
	v_mov_b64_e32 v[2:3], 0
	v_mov_b64_e32 v[4:5], 0
	v_mov_b64_e32 v[6:7], 0
	v_mov_b64_e32 v[16:17], 0
	v_mov_b64_e32 v[18:19], 0
	v_mov_b64_e32 v[20:21], 0
	v_mov_b64_e32 v[22:23], 0
	v_mov_b64_e32 v[34:35], 0
	v_mov_b64_e32 v[36:37], 0
	v_mov_b64_e32 v[38:39], 0
	v_mov_b64_e32 v[40:41], 0
	v_mov_b64_e32 v[50:51], 0
	v_mov_b64_e32 v[52:53], 0
	v_mov_b64_e32 v[54:55], 0
	v_mov_b64_e32 v[56:57], 0
	v_mov_b64_e32 v[8:9], 0
	v_mov_b64_e32 v[10:11], 0
	v_mov_b64_e32 v[12:13], 0
	v_mov_b64_e32 v[14:15], 0
	v_mov_b64_e32 v[24:25], 0
	v_mov_b64_e32 v[26:27], 0
	v_mov_b64_e32 v[28:29], 0
	v_mov_b64_e32 v[30:31], 0
	v_mov_b64_e32 v[42:43], 0
	v_mov_b64_e32 v[44:45], 0
	v_mov_b64_e32 v[46:47], 0
	v_mov_b64_e32 v[48:49], 0
	v_mov_b64_e32 v[58:59], 0
	v_mov_b64_e32 v[60:61], 0
	v_mov_b64_e32 v[62:63], 0
	v_mov_b64_e32 v[64:65], 0
	v_mov_b64_e32 v[66:67], 0
	v_mov_b64_e32 v[68:69], 0
	v_mov_b64_e32 v[70:71], 0
	v_mov_b64_e32 v[72:73], 0
	v_mov_b64_e32 v[82:83], 0
	v_mov_b64_e32 v[84:85], 0
	v_mov_b64_e32 v[86:87], 0
	v_mov_b64_e32 v[88:89], 0
	v_mov_b64_e32 v[98:99], 0
	v_mov_b64_e32 v[100:101], 0
	v_mov_b64_e32 v[102:103], 0
	v_mov_b64_e32 v[104:105], 0
	v_mov_b64_e32 v[114:115], 0
	v_mov_b64_e32 v[116:117], 0
	v_mov_b64_e32 v[118:119], 0
	v_mov_b64_e32 v[120:121], 0
	v_mov_b64_e32 v[74:75], 0
	v_mov_b64_e32 v[76:77], 0
	v_mov_b64_e32 v[78:79], 0
	v_mov_b64_e32 v[80:81], 0
	v_mov_b64_e32 v[90:91], 0
	v_mov_b64_e32 v[92:93], 0
	v_mov_b64_e32 v[94:95], 0
	v_mov_b64_e32 v[96:97], 0
	v_mov_b64_e32 v[106:107], 0
	v_mov_b64_e32 v[108:109], 0
	v_mov_b64_e32 v[110:111], 0
	v_mov_b64_e32 v[112:113], 0
	v_mov_b64_e32 v[126:127], 0
	v_mov_b64_e32 v[128:129], 0
	v_mov_b64_e32 v[134:135], 0
	v_mov_b64_e32 v[136:137], 0

.LBB0_1116:
	s_add_i32 s38, s37, -2
	s_add_u32 s39, s20, 0x100
	v_mov_b64_e32 v[0:1], 0
	s_addc_u32 s40, s21, 0
	s_mov_b32 s22, 0
	v_mov_b64_e32 v[2:3], 0
	v_mov_b64_e32 v[4:5], 0
	v_mov_b64_e32 v[6:7], 0
	v_mov_b64_e32 v[16:17], 0
	v_mov_b64_e32 v[18:19], 0
	v_mov_b64_e32 v[20:21], 0
	v_mov_b64_e32 v[22:23], 0
	v_mov_b64_e32 v[34:35], 0
	v_mov_b64_e32 v[36:37], 0
	v_mov_b64_e32 v[38:39], 0
	v_mov_b64_e32 v[40:41], 0
	v_mov_b64_e32 v[50:51], 0
	v_mov_b64_e32 v[52:53], 0
	v_mov_b64_e32 v[54:55], 0
	v_mov_b64_e32 v[56:57], 0
	v_mov_b64_e32 v[8:9], 0
	v_mov_b64_e32 v[10:11], 0
	v_mov_b64_e32 v[12:13], 0
	v_mov_b64_e32 v[14:15], 0
	v_mov_b64_e32 v[24:25], 0
	v_mov_b64_e32 v[26:27], 0
	v_mov_b64_e32 v[28:29], 0
	v_mov_b64_e32 v[30:31], 0
	v_mov_b64_e32 v[42:43], 0
	v_mov_b64_e32 v[44:45], 0
	v_mov_b64_e32 v[46:47], 0
	v_mov_b64_e32 v[48:49], 0
	v_mov_b64_e32 v[58:59], 0
	v_mov_b64_e32 v[60:61], 0
	v_mov_b64_e32 v[62:63], 0
	v_mov_b64_e32 v[64:65], 0
	v_mov_b64_e32 v[66:67], 0
	v_mov_b64_e32 v[68:69], 0
	v_mov_b64_e32 v[70:71], 0
	v_mov_b64_e32 v[72:73], 0
	v_mov_b64_e32 v[90:91], 0
	v_mov_b64_e32 v[92:93], 0
	v_mov_b64_e32 v[98:99], 0
	v_mov_b64_e32 v[100:101], 0
	v_mov_b64_e32 v[114:115], 0
	v_mov_b64_e32 v[116:117], 0
	v_mov_b64_e32 v[118:119], 0
	v_mov_b64_e32 v[120:121], 0
	v_mov_b64_e32 v[138:139], 0
	v_mov_b64_e32 v[140:141], 0
	v_mov_b64_e32 v[146:147], 0
	v_mov_b64_e32 v[148:149], 0
	v_mov_b64_e32 v[74:75], 0
	v_mov_b64_e32 v[76:77], 0
	v_mov_b64_e32 v[82:83], 0
	v_mov_b64_e32 v[84:85], 0
	v_mov_b64_e32 v[106:107], 0
	v_mov_b64_e32 v[108:109], 0
	v_mov_b64_e32 v[110:111], 0
	v_mov_b64_e32 v[112:113], 0
	v_mov_b64_e32 v[142:143], 0
	v_mov_b64_e32 v[144:145], 0
	v_mov_b64_e32 v[150:151], 0
	v_mov_b64_e32 v[152:153], 0
	v_mov_b64_e32 v[162:163], 0
	v_mov_b64_e32 v[164:165], 0
	v_mov_b64_e32 v[166:167], 0
	v_mov_b64_e32 v[168:169], 0

.LBB0_1275:
	s_add_u32 s3, s16, 0x100
	v_mov_b64_e32 v[0:1], 0
	s_addc_u32 s37, s17, 0
	s_mov_b32 s38, -2
	v_mov_b64_e32 v[2:3], 0
	v_mov_b64_e32 v[4:5], 0
	v_mov_b64_e32 v[6:7], 0
	v_mov_b64_e32 v[16:17], 0
	v_mov_b64_e32 v[18:19], 0
	v_mov_b64_e32 v[20:21], 0
	v_mov_b64_e32 v[22:23], 0
	v_mov_b64_e32 v[34:35], 0
	v_mov_b64_e32 v[36:37], 0
	v_mov_b64_e32 v[38:39], 0
	v_mov_b64_e32 v[40:41], 0
	v_mov_b64_e32 v[50:51], 0
	v_mov_b64_e32 v[52:53], 0
	v_mov_b64_e32 v[54:55], 0
	v_mov_b64_e32 v[56:57], 0
	v_mov_b64_e32 v[8:9], 0
	v_mov_b64_e32 v[10:11], 0
	v_mov_b64_e32 v[12:13], 0
	v_mov_b64_e32 v[14:15], 0
	v_mov_b64_e32 v[24:25], 0
	v_mov_b64_e32 v[26:27], 0
	v_mov_b64_e32 v[28:29], 0
	v_mov_b64_e32 v[30:31], 0
	v_mov_b64_e32 v[42:43], 0
	v_mov_b64_e32 v[44:45], 0
	v_mov_b64_e32 v[46:47], 0
	v_mov_b64_e32 v[48:49], 0
	v_mov_b64_e32 v[58:59], 0
	v_mov_b64_e32 v[60:61], 0
	v_mov_b64_e32 v[62:63], 0
	v_mov_b64_e32 v[64:65], 0
	v_mov_b64_e32 v[66:67], 0
	v_mov_b64_e32 v[68:69], 0
	v_mov_b64_e32 v[70:71], 0
	v_mov_b64_e32 v[72:73], 0
	v_mov_b64_e32 v[82:83], 0
	v_mov_b64_e32 v[84:85], 0
	v_mov_b64_e32 v[86:87], 0
	v_mov_b64_e32 v[88:89], 0
	v_mov_b64_e32 v[98:99], 0
	v_mov_b64_e32 v[100:101], 0
	v_mov_b64_e32 v[102:103], 0
	v_mov_b64_e32 v[104:105], 0
	v_mov_b64_e32 v[114:115], 0
	v_mov_b64_e32 v[116:117], 0
	v_mov_b64_e32 v[118:119], 0
	v_mov_b64_e32 v[120:121], 0
	v_mov_b64_e32 v[74:75], 0
	v_mov_b64_e32 v[76:77], 0
	v_mov_b64_e32 v[78:79], 0
	v_mov_b64_e32 v[80:81], 0
	v_mov_b64_e32 v[90:91], 0
	v_mov_b64_e32 v[92:93], 0
	v_mov_b64_e32 v[94:95], 0
	v_mov_b64_e32 v[96:97], 0
	v_mov_b64_e32 v[106:107], 0
	v_mov_b64_e32 v[108:109], 0
	v_mov_b64_e32 v[110:111], 0
	v_mov_b64_e32 v[112:113], 0
	v_mov_b64_e32 v[122:123], 0
	v_mov_b64_e32 v[124:125], 0
	v_mov_b64_e32 v[126:127], 0
	v_mov_b64_e32 v[128:129], 0

.LBB0_1364:
	s_add_i32 s43, s42, -2
	s_add_u32 s44, s12, 0x100
	v_mov_b64_e32 v[0:1], 0
	s_addc_u32 s45, s13, 0
	s_mov_b32 s14, 0
	v_mov_b64_e32 v[2:3], 0
	v_mov_b64_e32 v[4:5], 0
	v_mov_b64_e32 v[6:7], 0
	v_mov_b64_e32 v[16:17], 0
	v_mov_b64_e32 v[18:19], 0
	v_mov_b64_e32 v[20:21], 0
	v_mov_b64_e32 v[22:23], 0
	v_mov_b64_e32 v[34:35], 0
	v_mov_b64_e32 v[36:37], 0
	v_mov_b64_e32 v[38:39], 0
	v_mov_b64_e32 v[40:41], 0
	v_mov_b64_e32 v[50:51], 0
	v_mov_b64_e32 v[52:53], 0
	v_mov_b64_e32 v[54:55], 0
	v_mov_b64_e32 v[56:57], 0
	v_mov_b64_e32 v[8:9], 0
	v_mov_b64_e32 v[10:11], 0
	v_mov_b64_e32 v[12:13], 0
	v_mov_b64_e32 v[14:15], 0
	v_mov_b64_e32 v[24:25], 0
	v_mov_b64_e32 v[26:27], 0
	v_mov_b64_e32 v[28:29], 0
	v_mov_b64_e32 v[30:31], 0
	v_mov_b64_e32 v[42:43], 0
	v_mov_b64_e32 v[44:45], 0
	v_mov_b64_e32 v[46:47], 0
	v_mov_b64_e32 v[48:49], 0
	v_mov_b64_e32 v[58:59], 0
	v_mov_b64_e32 v[60:61], 0
	v_mov_b64_e32 v[62:63], 0
	v_mov_b64_e32 v[64:65], 0
	v_mov_b64_e32 v[66:67], 0
	v_mov_b64_e32 v[68:69], 0
	v_mov_b64_e32 v[70:71], 0
	v_mov_b64_e32 v[72:73], 0
	v_mov_b64_e32 v[82:83], 0
	v_mov_b64_e32 v[84:85], 0
	v_mov_b64_e32 v[86:87], 0
	v_mov_b64_e32 v[88:89], 0
	v_mov_b64_e32 v[98:99], 0
	v_mov_b64_e32 v[100:101], 0
	v_mov_b64_e32 v[102:103], 0
	v_mov_b64_e32 v[104:105], 0
	v_mov_b64_e32 v[118:119], 0
	v_mov_b64_e32 v[120:121], 0
	v_mov_b64_e32 v[126:127], 0
	v_mov_b64_e32 v[128:129], 0
	v_mov_b64_e32 v[74:75], 0
	v_mov_b64_e32 v[76:77], 0
	v_mov_b64_e32 v[78:79], 0
	v_mov_b64_e32 v[80:81], 0
	v_mov_b64_e32 v[90:91], 0
	v_mov_b64_e32 v[92:93], 0
	v_mov_b64_e32 v[94:95], 0
	v_mov_b64_e32 v[96:97], 0
	v_mov_b64_e32 v[122:123], 0
	v_mov_b64_e32 v[124:125], 0
	v_mov_b64_e32 v[130:131], 0
	v_mov_b64_e32 v[132:133], 0
	v_mov_b64_e32 v[142:143], 0
	v_mov_b64_e32 v[144:145], 0
	v_mov_b64_e32 v[146:147], 0
	v_mov_b64_e32 v[148:149], 0
